# dual-block attention without the static setprio for waves 4-7
# baseline (speedup 1.0000x reference)
; #define LAS __attribute__((address_space(3)))
; __device__ __forceinline__ int opaque_tid() { int t = threadIdx.x; asm volatile("" : "+v"(t)); return t; }
; __device__ __forceinline__ int v_st_nat(int k, int c) { return ((k >> 3) * 2 + (c >> 5)) * 512 + ((k & 7) * 32 + (c & 31)) * 2; }
; __device__ __forceinline__ int v_rd_base(int lane) { return ((lane & 3) << 3) | (((lane >> 2) & 3) << 6) | (((lane >> 4) & 1) << 5) | (((lane >> 5) & 1) << 8); }
; #define AT_LOAD(K0, K1, V0, V1, T) do { const size_t e_ = (size_t)(128 * (T) + sr) * 64 + sc; \
;         K0 = *(const bf16x8*)(kcp + e_); V0 = *(const bf16x8*)(vcp + e_); K1 = *(const bf16x8*)(kcp + e_ + 64 * 64); V1 = *(const bf16x8*)(vcp + e_ + 64 * 64); } while (0)
; #define AT_STORE(K0, K1, V0, V1, BUF) do { *(LAS bf16x8*)(lds + AT_K + (BUF) * AT_KB + kst0) = K0; *(LAS bf16x8*)(lds + AT_K + (BUF) * AT_KB + kst1) = K1; \
;         *(LAS bf16x8*)(lds + AT_V + (BUF) * AT_VB + vst0) = V0; *(LAS bf16x8*)(lds + AT_V + (BUF) * AT_VB + vst1) = V1; } while (0)
; template <int VAR>
; __device__ __forceinline__ void attn_unit(const Args& a, int l, int b, int h, int qrow0  , bool ctxu, const bf16* Z, bf16* Y, LAS unsigned char* lds) {
;     const int tid = opaque_tid(), lane = tid & 63, wave = __builtin_amdgcn_readfirstlane(tid >> 6), r32 = lane & 31, hi = lane >> 5;
;     const int comp = wave >> 2, wq = wave & 3;
;     const int NT = ctxu ? 2 : 66;
;     const bf16* kcp = (const bf16*)(a.ws + WS_KC) + (size_t)(b * 4 + h) * 8448 * 64; const bf16* vcp = (const bf16*)(a.ws + WS_VC) + (size_t)(b * 4 + h) * 8448 * 64;
;     bf16x8 q0, q1;
;     { const bf16* qp = Z + (size_t)(qrow0 + wq * 32 + r32) * DIN + 512 + h * 64 + comp * 32 + hi * 8; q0 = *(const bf16x8*)(qp); q1 = *(const bf16x8*)(qp + 16); }
;     const int sr = tid >> 3, sc = (tid & 7) * 8;
;     const int kst0 = sr * 144 + sc * 2, kst1 = kst0 + 64 * 144, vst0 = v_st_nat(sr, sc), vst1 = v_st_nat(sr + 64, sc);
;     const int vb0 = (int)(unsigned)(uintptr_t)(lds + AT_V) + v_rd_base(lane);
;     LAS float* wsf = (LAS float*)(lds + AT_WS) + wave * 64;
;     f32x16 negm = f32x16{}, o0 = f32x16{}, o1 = f32x16{}, lacc = f32x16{};
;     float m = 0.f;
;     bf16x8 ka0, ka1, va0, va1, kb0, kb1, vb0_, vb1_;
;     ...
;     AT_LOAD(ka0, ka1, va0, va1, 0); AT_LOAD(kb0, kb1, vb0_, vb1_, 1); AT_STORE(ka0, ka1, va0, va1, 0);
.LBB0_431:
	v_mov_b32_e32 v79, 0
	v_readfirstlane_b32 s36, v230
	v_readfirstlane_b32 s37, v231
	s_mov_b32 s94, 1
	s_mov_b32 s95, 1
	s_mov_b32 s33, 0
	s_lshr_b32 s50, s29, 6
	s_lshl_b32 s51, s50, 10
	s_lshl_b32 s93, s50, 8
	s_lshl_b32 s50, s50, 3
	v_lshrrev_b32_e32 v132, 3, v227
	v_add_u32_e32 v132, s50, v132
	v_bfe_u32 v133, v132, 1, 3
	v_and_b32_e32 v134, 7, v227
	v_xor_b32_e32 v134, v134, v133
	v_lshlrev_b32_e32 v132, 7, v132
	v_lshl_or_b32 v158, v134, 4, v132
	v_add_u32_e32 v159, 0x2000, v158
	v_bfe_u32 v132, v227, 2, 3
	v_add_u32_e32 v132, s50, v132
	v_lshrrev_b32_e32 v133, 5, v227
	v_and_b32_e32 v134, 3, v227
	v_lshlrev_b32_e32 v133, 6, v133
	v_lshl_or_b32 v133, v134, 4, v133
	v_lshl_or_b32 v160, v132, 7, v133
	v_add_u32_e32 v161, 0x2000, v160
	s_lshl_b32 s50, s8, 2
	v_add_u32_e32 v132, s50, v248
	v_bfe_u32 v133, v247, 1, 3
	v_xor_b32_e32 v132, v132, v133
	v_lshlrev_b32_e32 v133, 7, v247
	v_lshl_or_b32 v144, v132, 4, v133
	v_xor_b32_e32 v145, 32, v144
	v_add_u32_e32 v146, 0x3000, v249
	s_add_u32 s93, s93, 0x19800
	v_lshlrev_b32_e32 v132, 2, v247
	v_add_u32_e32 v148, s93, v132
	v_lshlrev_b32_e32 v132, 4, v248
	v_add_u32_e32 v147, s93, v132
	v_mov_b32_e32 v80, 0
	v_mov_b32_e32 v200, 0
	v_mov_b32_e32 v81, 0
	v_mov_b32_e32 v201, 0
	v_mov_b32_e32 v82, 0
	v_mov_b32_e32 v202, 0
	v_mov_b32_e32 v83, 0
	v_mov_b32_e32 v203, 0
	v_mov_b32_e32 v84, 0
	v_mov_b32_e32 v204, 0
	v_mov_b32_e32 v85, 0
	v_mov_b32_e32 v205, 0
	v_mov_b32_e32 v86, 0
	v_mov_b32_e32 v206, 0
	v_mov_b32_e32 v87, 0
	v_mov_b32_e32 v207, 0
	v_mov_b32_e32 v88, 0
	v_mov_b32_e32 v208, 0
	v_mov_b32_e32 v89, 0
	v_mov_b32_e32 v209, 0
	v_mov_b32_e32 v90, 0
	v_mov_b32_e32 v210, 0
	v_mov_b32_e32 v91, 0
	v_mov_b32_e32 v211, 0
	v_mov_b32_e32 v92, 0
	v_mov_b32_e32 v212, 0
	v_mov_b32_e32 v93, 0
	v_mov_b32_e32 v213, 0
	v_mov_b32_e32 v94, 0
	v_mov_b32_e32 v214, 0
	v_mov_b32_e32 v95, 0
	v_mov_b32_e32 v215, 0
	v_mov_b32_e32 v128, 0
	v_mov_b32_e32 v129, 0
	v_mov_b32_e32 v130, 0
	v_mov_b32_e32 v131, 0
	v_mov_b32_e32 v149, 0
	s_sub_u32 s36, s36, s51
	s_subb_u32 s37, s37, 0
	s_add_u32 s48, s36, 0x1d200000
	s_addc_u32 s49, s37, 0
	s_add_u32 s36, s36, 0x1c000000
	s_addc_u32 s37, s37, 0
	s_waitcnt lgkmcnt(0)
	s_add_u32 m0, s51, 0x0
	s_nop 0
	global_load_lds_dwordx4 v158, s[36:37]
	s_add_u32 m0, s51, 0x2000
	s_nop 0
	global_load_lds_dwordx4 v159, s[36:37]
	s_add_u32 m0, s51, 0xc000
	s_nop 0
	global_load_lds_dwordx4 v160, s[48:49]
	s_add_u32 m0, s51, 0xe000
	s_nop 0
	global_load_lds_dwordx4 v161, s[48:49]
	s_add_u32 s36, s36, 0x4000
	s_addc_u32 s37, s37, 0
	s_add_u32 s48, s48, 0x4000
	s_addc_u32 s49, s49, 0
	s_add_u32 m0, s51, 0x4000
	s_nop 0
	global_load_lds_dwordx4 v158, s[36:37]
	s_add_u32 m0, s51, 0x6000
	s_nop 0
	global_load_lds_dwordx4 v159, s[36:37]
	s_add_u32 m0, s51, 0x10000
	s_nop 0
	global_load_lds_dwordx4 v160, s[48:49]
	s_add_u32 m0, s51, 0x12000
	s_nop 0
	global_load_lds_dwordx4 v161, s[48:49]
	s_add_u32 s36, s36, 0x4000
	s_addc_u32 s37, s37, 0
	s_add_u32 s48, s48, 0x4000
	s_addc_u32 s49, s49, 0
	s_waitcnt vmcnt(4)
	s_barrier
	s_add_u32 m0, s51, 0x8000
	s_nop 0
	global_load_lds_dwordx4 v158, s[36:37]
	s_add_u32 m0, s51, 0xa000
	s_nop 0
	global_load_lds_dwordx4 v159, s[36:37]
	s_add_u32 m0, s51, 0x14000
	s_nop 0
	global_load_lds_dwordx4 v160, s[48:49]
	s_add_u32 m0, s51, 0x16000
	s_nop 0
	global_load_lds_dwordx4 v161, s[48:49]
	s_add_u32 s36, s36, 0x4000
	s_addc_u32 s37, s37, 0
	s_add_u32 s48, s48, 0x4000
	s_addc_u32 s49, s49, 0
	ds_read_b128 v[48:51], v144 offset:0
	ds_read_b128 v[52:55], v145 offset:0
	ds_read_b128 v[56:59], v144 offset:4096
	ds_read_b128 v[60:63], v145 offset:4096

; #define AT_LOAD(K0, K1, V0, V1, T) do { const size_t e_ = (size_t)(128 * (T) + sr) * 64 + sc; \
;         K0 = *(const bf16x8*)(kcp + e_); V0 = *(const bf16x8*)(vcp + e_); K1 = *(const bf16x8*)(kcp + e_ + 64 * 64); V1 = *(const bf16x8*)(vcp + e_ + 64 * 64); } while (0)
; #define AT_STORE(K0, K1, V0, V1, BUF) do { *(LAS bf16x8*)(lds + AT_K + (BUF) * AT_KB + kst0) = K0; *(LAS bf16x8*)(lds + AT_K + (BUF) * AT_KB + kst1) = K1; \
;         *(LAS bf16x8*)(lds + AT_V + (BUF) * AT_VB + vst0) = V0; *(LAS bf16x8*)(lds + AT_V + (BUF) * AT_VB + vst1) = V1; } while (0)
; template <int VAR>
; __device__ __forceinline__ void attn_unit(const Args& a, int l, int b, int h, int qrow0  , bool ctxu, const bf16* Z, bf16* Y, LAS unsigned char* lds) {
;     ...
;     for (int t = 0; t < NT; t += 2) {
;         __syncthreads();
;         if (t + 2 < NT) AT_LOAD(ka0, ka1, va0, va1, t + 2);
;         attn_tile(Kb0, vb0, q0, q1, negm, m, o0, o1, lacc, t == 0, wsf, r32, hi);
;         AT_STORE(kb0, kb1, vb0_, vb1_, 1);
;         __syncthreads();
;         if (t + 3 < NT) AT_LOAD(kb0, kb1, vb0_, vb1_, t + 3);
;         attn_tile(Kb0 + AT_KB, vb0 + AT_VB, q0, q1, negm, m, o0, o1, lacc, false, wsf, r32, hi);
;         if (t + 2 < NT) AT_STORE(ka0, ka1, va0, va1, 0);
;     }
.Lat_ndg5:
	ds_read_b128 v[48:51], v144 offset:0
	ds_read_b128 v[52:55], v145 offset:0
	ds_read_b128 v[56:59], v144 offset:4096
	ds_read_b128 v[60:63], v145 offset:4096
	v_mfma_f32_32x32x16_bf16 v[80:95], v[162:165], v[192:195], v[80:95]
	v_mfma_f32_32x32x16_bf16 v[200:215], v[162:165], v[196:199], v[200:215]
	s_add_u32 s33, s33, 1
	s_cmp_lt_u32 s33, 22
	s_cbranch_scc1 .Lat_loop
	v_add_f32_e32 v132, v128, v129
	v_mov_b32_e32 v133, v132
	s_nop 1
	v_permlane32_swap_b32_e32 v132, v133
	v_add_f32_e32 v135, v132, v133
	v_add_f32_e32 v132, v130, v131
	v_mov_b32_e32 v133, v132
	s_nop 1
	v_permlane32_swap_b32_e32 v132, v133
	v_add_f32_e32 v130, v132, v133
	s_nop 7
	s_waitcnt lgkmcnt(0)
	ds_write_b32 v148, v135
	s_waitcnt lgkmcnt(0)
	ds_read_b128 v[32:35], v147 offset:0
	ds_read_b128 v[36:39], v147 offset:32
	ds_read_b128 v[40:43], v147 offset:64
	ds_read_b128 v[44:47], v147 offset:96
	s_waitcnt lgkmcnt(0)
	s_mov_b32 s93, 0
	s_waitcnt vmcnt(0)
	s_branch .LBB0_459
